# MLA loop: counted lgkmcnt waits so freshly issued V fragment reads are not waited for early
# speedup vs baseline: 1.0291x; 1.0047x over previous
; #define MFMA32(a, b, c) __builtin_amdgcn_mfma_f32_32x32x16_bf16((a), (b), (c), 0, 0, 0)
; DI int crow(int r, int hi) { return (r & 3) + 8 * (r >> 2) + 4 * hi; }
; #define VFRAG(dst, kk_) do { _Pragma("unroll") for (int mt = 0; mt < 4; ++mt) dst[mt] = *(const LAS bf16x8*)(vb + (32 * mt + r32) * VP + 16 * (kk_) + 8 * hf); } while (0)
; #define KFRAG(da, dc, ks_) do { da = *(const LAS bf16x8*)(kb + r32 * KP + 16 * (ks_) + 8 * hf); dc = *(const LAS bf16x8*)(kb + (32 + r32) * KP + 16 * (ks_) + 8 * hf); } while (0)
; DI void mla_attn_phase(LAS unsigned char* lds, const bf16_t* Qg, const bf16_t* Kg, const bf16_t* Vtg, bf16_t* MIX) {
;     ...
;                     bf16x8 ka0, kc0_, ka1, kc1_;
;                     KFRAG(ka0, kc0_, 0); KFRAG(ka1, kc1_, 1);
;                     __builtin_amdgcn_sched_barrier(0);
;                     f32x16 s0, s1;
; #pragma unroll
;                     for (int i = 0; i < 16; ++i) { s0[i] = 0.f; s1[i] = 0.f; }
;                     s0 = MFMA32(ka0, qf[0], s0); s1 = MFMA32(kc0_, qf[0], s1); KFRAG(ka0, kc0_, 2); __builtin_amdgcn_sched_barrier(0);
;                     s0 = MFMA32(ka1, qf[1], s0); s1 = MFMA32(kc1_, qf[1], s1); KFRAG(ka1, kc1_, 3); __builtin_amdgcn_sched_barrier(0);
;                     s0 = MFMA32(ka0, qf[2], s0); s1 = MFMA32(kc0_, qf[2], s1); KFRAG(ka0, kc0_, 4); __builtin_amdgcn_sched_barrier(0);
;                     s0 = MFMA32(ka1, qf[3], s0); s1 = MFMA32(kc1_, qf[3], s1); KFRAG(ka1, kc1_, 5); __builtin_amdgcn_sched_barrier(0);
;                     s0 = MFMA32(ka0, qf[4], s0); s1 = MFMA32(kc0_, qf[4], s1); s0 = MFMA32(ka1, qf[5], s0); s1 = MFMA32(kc1_, qf[5], s1);
;     ...
;                     bf16x8 vfa[4], vfb[4];
;                     VFRAG(vfa, 0); VFRAG(vfb, 1);
;                     __builtin_amdgcn_sched_barrier(0);
;                     if (kt >= 4 * qb) { const int qpos = q0 + r32;
; #pragma unroll
;                         for (int i = 0; i < 16; ++i) { const int key0 = 64 * kt + crow(i, hf); if (key0 > qpos) s0[i] = -INFINITY; if (key0 + 32 > qpos) s1[i] = -INFINITY; } }
.LBB0_361:
	s_cmp_gt_i32 s40, s39
	s_cbranch_scc1 .Lmla_mid
	s_lshl_b32 s30, s41, 15
	s_add_i32 s30, s30, 0
	v_lshlrev_b32_e32 v0, 1, v166
	v_add_u32_e32 v1, s30, v0
	v_add_u32_e32 v3, v1, v230
	ds_read_b128 v[4:7], v3
	ds_read_b128 v[8:11], v3 offset:32
	ds_read_b128 v[12:15], v3 offset:6656
	ds_read_b128 v[136:139], v3 offset:6688
	s_waitcnt lgkmcnt(0)
	v_mfma_f32_32x32x16_bf16 v[80:95], v[4:7], v[112:115], 0
	ds_read_b128 v[4:7], v3 offset:64
	ds_read_b128 v[140:143], v3 offset:6720
	v_mfma_f32_32x32x16_bf16 v[80:95], v[8:11], v[116:119], v[80:95]
	ds_read_b128 v[8:11], v3 offset:96
	ds_read_b128 v[144:147], v3 offset:6752
	s_waitcnt lgkmcnt(0)
	v_mfma_f32_32x32x16_bf16 v[80:95], v[4:7], v[120:123], v[80:95]
	ds_read_b128 v[4:7], v3 offset:128
	ds_read_b128 v[148:151], v3 offset:6784
	v_mfma_f32_32x32x16_bf16 v[80:95], v[8:11], v[124:127], v[80:95]
	ds_read_b128 v[8:11], v3 offset:160
	ds_read_b128 v[236:239], v3 offset:6816
	v_mfma_f32_32x32x16_bf16 v[96:111], v[12:15], v[112:115], 0
	v_add_u32_e32 v1, v1, v232
	v_mfma_f32_32x32x16_bf16 v[96:111], v[136:139], v[116:119], v[96:111]
	v_mfma_f32_32x32x16_bf16 v[96:111], v[140:143], v[120:123], v[96:111]
	v_mfma_f32_32x32x16_bf16 v[96:111], v[144:147], v[124:127], v[96:111]
	ds_read_b128 v[144:147], v1 offset:13312
	ds_read_b128 v[140:143], v1 offset:17920
	s_waitcnt lgkmcnt(2)
	v_mfma_f32_32x32x16_bf16 v[80:95], v[4:7], v[128:131], v[80:95]
	v_mfma_f32_32x32x16_bf16 v[96:111], v[148:151], v[128:131], v[96:111]
	ds_read_b128 v[148:151], v1 offset:22528
	ds_read_b128 v[152:155], v1 offset:27136
	v_add3_u32 v1, s30, v232, v0
	v_mfma_f32_32x32x16_bf16 v[80:95], v[8:11], v[132:135], v[80:95]
	ds_read_b128 v[136:139], v1 offset:13344
	ds_read_b128 v[12:15], v1 offset:17952
	ds_read_b128 v[4:7], v1 offset:22560
	ds_read_b128 v[8:11], v1 offset:27168
	v_mfma_f32_32x32x16_bf16 v[96:111], v[236:239], v[132:135], v[96:111]
	s_cmp_lt_i32 s42, s8
	s_cbranch_scc1 .LBB0_364
	v_add_u32_e32 v0, s40, v231
	v_add_u32_e32 v3, 32, v0
	v_cmp_le_i32_e32 vcc, v3, v167
	v_add_u32_e32 v3, 33, v0
	s_nop 5
	v_cndmask_b32_e32 v96, v229, v96, vcc
	v_cmp_lt_i32_e32 vcc, v0, v167
	s_nop 1
	v_cndmask_b32_e32 v81, v229, v81, vcc
	v_cmp_le_i32_e32 vcc, v0, v167
	s_nop 1
	v_cndmask_b32_e32 v80, v229, v80, vcc
	v_cmp_le_i32_e32 vcc, v3, v167
	v_add_u32_e32 v3, 2, v0
	s_nop 0
	v_cndmask_b32_e32 v97, v229, v97, vcc
	v_cmp_le_i32_e32 vcc, v3, v167
	v_add_u32_e32 v3, 34, v0
	s_nop 0
	v_cndmask_b32_e32 v82, v229, v82, vcc
	v_cmp_le_i32_e32 vcc, v3, v167
	v_add_u32_e32 v3, 3, v0
	s_nop 0
	v_cndmask_b32_e32 v98, v229, v98, vcc
	v_cmp_le_i32_e32 vcc, v3, v167
	v_add_u32_e32 v3, 35, v0
	s_nop 0
	v_cndmask_b32_e32 v83, v229, v83, vcc
	v_cmp_le_i32_e32 vcc, v3, v167
	v_add_u32_e32 v3, 8, v0
	s_nop 0
	v_cndmask_b32_e32 v99, v229, v99, vcc
	v_cmp_le_i32_e32 vcc, v3, v167
	v_add_u32_e32 v3, 40, v0
	s_nop 0
	v_cndmask_b32_e32 v84, v229, v84, vcc
	v_cmp_le_i32_e32 vcc, v3, v167
	v_add_u32_e32 v3, 9, v0
	s_nop 0
	v_cndmask_b32_e32 v100, v229, v100, vcc
	v_cmp_le_i32_e32 vcc, v3, v167
	v_add_u32_e32 v3, 41, v0
	s_nop 0
	v_cndmask_b32_e32 v85, v229, v85, vcc
	v_cmp_le_i32_e32 vcc, v3, v167
	v_add_u32_e32 v3, 10, v0
	s_nop 0
	v_cndmask_b32_e32 v101, v229, v101, vcc
	v_cmp_le_i32_e32 vcc, v3, v167
	v_add_u32_e32 v3, 42, v0
	s_nop 0
	v_cndmask_b32_e32 v86, v229, v86, vcc
	v_cmp_le_i32_e32 vcc, v3, v167
	v_add_u32_e32 v3, 11, v0
	s_nop 0
	v_cndmask_b32_e32 v102, v229, v102, vcc
	v_cmp_le_i32_e32 vcc, v3, v167
	v_add_u32_e32 v3, 43, v0
	s_nop 0
	v_cndmask_b32_e32 v87, v229, v87, vcc
	v_cmp_le_i32_e32 vcc, v3, v167
	v_add_u32_e32 v3, 16, v0
	s_nop 0
	v_cndmask_b32_e32 v103, v229, v103, vcc
	v_cmp_le_i32_e32 vcc, v3, v167
	v_add_u32_e32 v3, 48, v0
	s_nop 0
	v_cndmask_b32_e32 v88, v229, v88, vcc
	v_cmp_le_i32_e32 vcc, v3, v167
	v_add_u32_e32 v3, 17, v0
	s_nop 0
	v_cndmask_b32_e32 v104, v229, v104, vcc
	v_cmp_le_i32_e32 vcc, v3, v167
	v_add_u32_e32 v3, 49, v0
	s_nop 0
	v_cndmask_b32_e32 v89, v229, v89, vcc
	v_cmp_le_i32_e32 vcc, v3, v167
	v_add_u32_e32 v3, 18, v0
	s_nop 0
	v_cndmask_b32_e32 v105, v229, v105, vcc
	v_cmp_le_i32_e32 vcc, v3, v167
	v_add_u32_e32 v3, 50, v0
	s_nop 0
	v_cndmask_b32_e32 v90, v229, v90, vcc
	v_cmp_le_i32_e32 vcc, v3, v167
	v_add_u32_e32 v3, 19, v0
	s_nop 0
	v_cndmask_b32_e32 v106, v229, v106, vcc
	v_cmp_le_i32_e32 vcc, v3, v167
	v_add_u32_e32 v3, 51, v0
	s_nop 0
	v_cndmask_b32_e32 v91, v229, v91, vcc
	v_cmp_le_i32_e32 vcc, v3, v167
	v_add_u32_e32 v3, 24, v0
	s_nop 0
	v_cndmask_b32_e32 v107, v229, v107, vcc
	v_cmp_le_i32_e32 vcc, v3, v167
	v_add_u32_e32 v3, 56, v0
	s_nop 0
	v_cndmask_b32_e32 v92, v229, v92, vcc
	v_cmp_le_i32_e32 vcc, v3, v167
	v_add_u32_e32 v3, 25, v0
	s_nop 0
	v_cndmask_b32_e32 v108, v229, v108, vcc
	v_cmp_le_i32_e32 vcc, v3, v167
	v_add_u32_e32 v3, 57, v0
	s_nop 0
	v_cndmask_b32_e32 v93, v229, v93, vcc
	v_cmp_le_i32_e32 vcc, v3, v167
	v_add_u32_e32 v3, 26, v0
	s_nop 0
	v_cndmask_b32_e32 v109, v229, v109, vcc
	v_cmp_le_i32_e32 vcc, v3, v167
	v_add_u32_e32 v3, 58, v0
	s_nop 0
	v_cndmask_b32_e32 v94, v229, v94, vcc
	v_cmp_le_i32_e32 vcc, v3, v167
	v_add_u32_e32 v3, 27, v0
	v_add_u32_e32 v0, 59, v0
	v_cndmask_b32_e32 v110, v229, v110, vcc
	v_cmp_le_i32_e32 vcc, v3, v167
	s_nop 1
	v_cndmask_b32_e32 v95, v229, v95, vcc
	v_cmp_le_i32_e32 vcc, v0, v167
	s_nop 1
	v_cndmask_b32_e32 v111, v229, v111, vcc

; DI unsigned pk2(float lo, float hi) { const f32x2_t v = {lo, hi}; const bf16x2_t b = __builtin_convertvector(v, bf16x2_t); return __builtin_bit_cast(unsigned, b); }
; DI void mla_attn_phase(LAS unsigned char* lds, const bf16_t* Qg, const bf16_t* Kg, const bf16_t* Vtg, bf16_t* MIX) {
;     ...
;                     const float m_new = fmaxf(m_run, mx), alpha = __builtin_amdgcn_exp2f(m_run - m_new); m_run = m_new;
;                     float sum = 0.f;
; #pragma unroll
;                     for (int i = 0; i < 16; ++i) { s0[i] = __builtin_amdgcn_exp2f(s0[i] - m_new); s1[i] = __builtin_amdgcn_exp2f(s1[i] - m_new); sum += s0[i] + s1[i]; }
;                     l_run = l_run * alpha + sum;
;                     if (__any(alpha != 1.f)) {
; #pragma unroll
;                         for (int mt = 0; mt < 4; ++mt)
; #pragma unroll
;                             for (int i = 0; i < 16; ++i) o[mt][i] *= alpha; }
;                     bf16x8 pf[4];
; #pragma unroll
;                     for (int sp = 0; sp < 2; ++sp) { u32x4 p0, p1;
; #pragma unroll
;                         for (int j = 0; j < 4; ++j) { p0[j] = pk2(s0[8 * sp + 2 * j], s0[8 * sp + 2 * j + 1]); p1[j] = pk2(s1[8 * sp + 2 * j], s1[8 * sp + 2 * j + 1]); }
;                         pf[sp] = __builtin_bit_cast(bf16x8, p0); pf[2 + sp] = __builtin_bit_cast(bf16x8, p1); }
;                     __builtin_amdgcn_sched_barrier(0);
;                     MLA_PV();
.Lmla_mid_done:
	s_cmp_gt_i32 s40, s39
	s_cbranch_scc1 .LBB0_367
	v_sub_f32_e32 v80, v80, v3
	v_sub_f32_e32 v96, v96, v3
	v_exp_f32_e32 v80, v80
	v_exp_f32_e32 v96, v96
	v_sub_f32_e32 v81, v81, v3
	v_sub_f32_e32 v97, v97, v3
	v_exp_f32_e32 v81, v81
	v_exp_f32_e32 v97, v97
	v_sub_f32_e32 v82, v82, v3
	v_sub_f32_e32 v98, v98, v3
	v_exp_f32_e32 v82, v82
	v_exp_f32_e32 v98, v98
	v_sub_f32_e32 v83, v83, v3
	v_sub_f32_e32 v99, v99, v3
	v_exp_f32_e32 v83, v83
	v_exp_f32_e32 v99, v99
	v_add_f32_e32 v218, v80, v96
	v_sub_f32_e32 v84, v84, v3
	v_add_f32_e32 v218, 0, v218
	v_add_f32_e32 v219, v81, v97
	v_exp_f32_e32 v226, v84
	v_sub_f32_e32 v84, v100, v3
	v_add_f32_e32 v218, v219, v218
	v_add_f32_e32 v219, v82, v98
	v_exp_f32_e32 v100, v84
	v_sub_f32_e32 v84, v85, v3
	v_add_f32_e32 v218, v219, v218
	v_add_f32_e32 v219, v83, v99
	v_exp_f32_e32 v227, v84
	v_sub_f32_e32 v84, v101, v3
	v_sub_f32_e32 v86, v86, v3
	v_exp_f32_e32 v101, v84
	v_add_f32_e32 v84, v219, v218
	v_exp_f32_e32 v218, v86
	v_sub_f32_e32 v86, v102, v3
	v_exp_f32_e32 v102, v86
	v_sub_f32_e32 v86, v87, v3
	v_exp_f32_e32 v87, v86
	v_sub_f32_e32 v86, v103, v3
	v_exp_f32_e32 v103, v86
	v_sub_f32_e32 v86, v88, v3
	v_exp_f32_e32 v88, v86
	v_sub_f32_e32 v86, v104, v3
	v_exp_f32_e32 v104, v86
	v_sub_f32_e32 v86, v89, v3
	v_exp_f32_e32 v89, v86
	v_sub_f32_e32 v86, v105, v3
	v_exp_f32_e32 v105, v86
	v_sub_f32_e32 v86, v90, v3
	v_exp_f32_e32 v90, v86
	v_sub_f32_e32 v86, v106, v3
	v_exp_f32_e32 v106, v86
	v_sub_f32_e32 v86, v91, v3
	v_exp_f32_e32 v91, v86
	v_sub_f32_e32 v86, v107, v3
	v_exp_f32_e32 v107, v86
	v_sub_f32_e32 v86, v92, v3
	v_add_f32_e32 v85, v226, v100
	v_exp_f32_e32 v219, v86
	v_sub_f32_e32 v86, v108, v3
	v_add_f32_e32 v84, v85, v84
	v_add_f32_e32 v85, v227, v101
	v_exp_f32_e32 v108, v86
	v_sub_f32_e32 v86, v93, v3
	v_add_f32_e32 v84, v85, v84
	v_add_f32_e32 v85, v218, v102
	v_exp_f32_e32 v234, v86
	v_sub_f32_e32 v86, v109, v3
	v_add_f32_e32 v84, v85, v84
	v_add_f32_e32 v85, v87, v103
	v_exp_f32_e32 v109, v86
	v_sub_f32_e32 v86, v94, v3
	v_add_f32_e32 v84, v85, v84
	v_add_f32_e32 v85, v88, v104
	v_exp_f32_e32 v235, v86
	v_sub_f32_e32 v86, v110, v3
	v_add_f32_e32 v84, v85, v84
	v_add_f32_e32 v85, v89, v105
	v_exp_f32_e32 v110, v86
	v_sub_f32_e32 v86, v95, v3
	v_add_f32_e32 v84, v85, v84
	v_add_f32_e32 v85, v90, v106
	v_exp_f32_e32 v95, v86
	v_sub_f32_e32 v86, v111, v3
	v_add_f32_e32 v84, v85, v84
	v_add_f32_e32 v85, v91, v107
	v_exp_f32_e32 v111, v86
	v_add_f32_e32 v84, v85, v84
	v_add_f32_e32 v85, v219, v108
	v_add_f32_e32 v84, v85, v84
	v_add_f32_e32 v85, v234, v109
	v_add_f32_e32 v84, v85, v84
	v_add_f32_e32 v85, v235, v110
	v_add_f32_e32 v84, v85, v84
	v_add_f32_e32 v85, v95, v111
	v_add_f32_e32 v236, v85, v84
	v_fmac_f32_e32 v236, v233, v0
	v_cvt_pk_bf16_f32 v80, v80, v81
	v_cvt_pk_bf16_f32 v84, v96, v97
	v_cvt_pk_bf16_f32 v81, v82, v83
	v_cvt_pk_bf16_f32 v85, v98, v99
	v_cvt_pk_bf16_f32 v82, v226, v227
	v_cvt_pk_bf16_f32 v86, v100, v101
	v_cvt_pk_bf16_f32 v83, v218, v87
	v_cvt_pk_bf16_f32 v87, v102, v103
	v_cvt_pk_bf16_f32 v88, v88, v89
	v_cvt_pk_bf16_f32 v92, v104, v105
	v_cvt_pk_bf16_f32 v89, v90, v91
	v_cvt_pk_bf16_f32 v93, v106, v107
	v_cvt_pk_bf16_f32 v90, v219, v234
	v_cvt_pk_bf16_f32 v94, v108, v109
	v_cvt_pk_bf16_f32 v91, v235, v95
	v_cvt_pk_bf16_f32 v95, v110, v111
	s_waitcnt lgkmcnt(6)
	v_mfma_f32_32x32x16_bf16 v[64:79], v[144:147], v[80:83], v[64:79]
	v_mfma_f32_32x32x16_bf16 v[48:63], v[140:143], v[80:83], v[48:63]
	s_waitcnt lgkmcnt(0)
	v_mfma_f32_32x32x16_bf16 v[32:47], v[148:151], v[80:83], v[32:47]
	v_mfma_f32_32x32x16_bf16 v[16:31], v[152:155], v[80:83], v[16:31]
	ds_read_b128 v[80:83], v1 offset:13376
	ds_read_b128 v[96:99], v1 offset:17984
	ds_read_b128 v[100:103], v1 offset:22592
	ds_read_b128 v[104:107], v1 offset:27200
	v_mfma_f32_32x32x16_bf16 v[64:79], v[136:139], v[88:91], v[64:79]
	v_mfma_f32_32x32x16_bf16 v[48:63], v[12:15], v[88:91], v[48:63]
	v_mfma_f32_32x32x16_bf16 v[32:47], v[4:7], v[88:91], v[32:47]
	v_mfma_f32_32x32x16_bf16 v[16:31], v[8:11], v[88:91], v[16:31]
	ds_read_b128 v[4:7], v1 offset:13408
	ds_read_b128 v[8:11], v1 offset:18016
	ds_read_b128 v[12:15], v1 offset:22624
	ds_read_b128 v[88:91], v1 offset:27232
	s_waitcnt lgkmcnt(4)
	v_mfma_f32_32x32x16_bf16 v[64:79], v[80:83], v[84:87], v[64:79]
	v_mov_b32_e32 v233, v236
	v_mfma_f32_32x32x16_bf16 v[48:63], v[96:99], v[84:87], v[48:63]
	v_mfma_f32_32x32x16_bf16 v[32:47], v[100:103], v[84:87], v[32:47]
	v_mfma_f32_32x32x16_bf16 v[16:31], v[104:107], v[84:87], v[16:31]
	s_waitcnt lgkmcnt(0)
	v_mfma_f32_32x32x16_bf16 v[64:79], v[4:7], v[92:95], v[64:79]
	v_mfma_f32_32x32x16_bf16 v[48:63], v[8:11], v[92:95], v[48:63]
	v_mfma_f32_32x32x16_bf16 v[32:47], v[12:15], v[92:95], v[32:47]
	v_mfma_f32_32x32x16_bf16 v[16:31], v[88:91], v[92:95], v[16:31]
	s_branch .Lmla_tail
